# v51 + RWKV epilogue-operand loads issued a whole chunk ahead into own registers, counted vmcnt per wave class (tools_rwpipe)
# speedup vs baseline: 1.0073x; 1.0073x over previous
; __device__ __forceinline__ void rwkv_chunk_item(const P& p, const Ctx& c, int seg, int w, bool save) {
;     ...
;     auto eload = [&](int ch) { const size_t rr = (size_t)b * SEGT + ch * 16 + et;
;         e_g = *(const u32x2*)(SG + rr * DMIX + ech); e_v = *(const u32x2*)(SV + rr * DMIX + ech); e_z = *(const u32x2*)(P2 + rr * P2W + 512 + ech); e_rkr = BRKR[(rr * 24 + hh) * 4 + 2]; };
;     ...
;         } else eload(ch);
.LBB0_888:
	s_and_b64 vcc, exec, s[68:69]
	s_cbranch_vccz .Lrw_noeload
	v_lshl_add_u64 v[112:113], v[36:37], 0, s[12:13]
	v_add_co_u32_e32 v114, vcc, 0xe900000, v112
	s_nop 1
	v_addc_co_u32_e32 v115, vcc, 0, v113, vcc
	v_add_co_u32_e32 v112, vcc, 0xdd00000, v112
	s_nop 1
	v_addc_co_u32_e32 v113, vcc, 0, v113, vcc
	global_load_dwordx2 v[104:105], v[114:115], off
	global_load_dwordx2 v[106:107], v[112:113], off
	v_lshl_add_u64 v[112:113], v[34:35], 0, s[12:13]
	global_load_dwordx2 v[108:109], v[112:113], off
	v_lshl_add_u64 v[112:113], v[32:33], 0, s[12:13]
	global_load_dword v110, v[112:113], off

; #define LAS __attribute__((address_space(3)))
; __device__ __forceinline__ void rwkv_chunk_item(const P& p, const Ctx& c, int seg, int w, bool save) {
;     ...
;     auto lstore = [&](int pb, int tidv) { const int t = tidv >> 5, j0 = (tidv & 31) * 2;
;         LAS bf16_t* EA = (LAS bf16_t*)(OB + pb * OPB + O_EA); LAS bf16_t* EB = (LAS bf16_t*)(OB + pb * OPB + O_EB); LAS bf16_t* EBT = (LAS bf16_t*)(OB + pb * OPB + O_EBT);
;         LAS bf16_t* UV = (LAS bf16_t*)(OB + pb * OPB + O_UV); LAS float* GT = (LAS float*)(OB + pb * OPB + O_GT);
;         *(LAS unsigned*)(EA + t * 72 + j0) = ga; *(LAS unsigned*)(EA + (16 + t) * 72 + j0) = gr;
;         *(LAS unsigned*)(EB + t * 72 + j0) = gb; *(LAS unsigned*)(EB + (16 + t) * 72 + j0) = gk;
;         EBT[j0 * 40 + t] = (bf16_t)(gb & 0xFFFFu); EBT[(j0 + 1) * 40 + t] = (bf16_t)(gb >> 16); EBT[j0 * 40 + 16 + t] = (bf16_t)(gk & 0xFFFFu); EBT[(j0 + 1) * 40 + 16 + t] = (bf16_t)(gk >> 16);
;         UV[j0 * 40 + 16 + t] = (bf16_t)(gv & 0xFFFFu); UV[(j0 + 1) * 40 + 16 + t] = (bf16_t)(gv >> 16); UV[j0 * 40 + t] = 0; UV[(j0 + 1) * 40 + t] = 0;
;         if (tidv < 64) GT[tidv] = gg; };
.Lrw_early_skip:
	s_cmp_eq_u32 s86, 31
	s_cselect_b64 s[4:5], -1, 0
	s_and_b64 vcc, exec, s[4:5]
	v_ashrrev_i32_e32 v46, 5, v44
	v_lshlrev_b32_e32 v45, 1, v44
	v_cmp_gt_i32_e64 s[2:3], 64, v44
	s_cbranch_vccnz .LBB0_931
	s_xor_b32 s78, s87, 1
	v_and_b32_e32 v47, 62, v45
	s_mulk_i32 s78, 0x5c00
	s_add_i32 s89, s78, 0
	v_mul_lo_u32 v48, v46, s63
	v_lshlrev_b32_e32 v49, 1, v47
	v_mad_u32_u24 v47, v47, 40, v46
	v_add3_u32 v48, s89, v48, v49
	v_lshl_add_u32 v47, v47, 1, s89
	s_and_b64 vcc, exec, s[68:69]
	s_cbranch_vccz .Lrw_w3_all
	s_cmp_eq_u32 s86, 0
	s_cbranch_scc1 .Lrw_w3_first
	s_waitcnt vmcnt(5)
	s_branch .Lrw_w3_done
.Lrw_w3_first:
	s_waitcnt vmcnt(4)
	s_branch .Lrw_w3_done

; #define LAS __attribute__((address_space(3)))
; __device__ __forceinline__ void rwkv_chunk_item(const P& p, const Ctx& c, int seg, int w, bool save) {
;     ...
;     auto lstore = [&](int pb, int tidv) { const int t = tidv >> 5, j0 = (tidv & 31) * 2;
;         LAS bf16_t* EA = (LAS bf16_t*)(OB + pb * OPB + O_EA); LAS bf16_t* EB = (LAS bf16_t*)(OB + pb * OPB + O_EB); LAS bf16_t* EBT = (LAS bf16_t*)(OB + pb * OPB + O_EBT);
;         LAS bf16_t* UV = (LAS bf16_t*)(OB + pb * OPB + O_UV); LAS float* GT = (LAS float*)(OB + pb * OPB + O_GT);
;         *(LAS unsigned*)(EA + t * 72 + j0) = ga; *(LAS unsigned*)(EA + (16 + t) * 72 + j0) = gr;
;         *(LAS unsigned*)(EB + t * 72 + j0) = gb; *(LAS unsigned*)(EB + (16 + t) * 72 + j0) = gk;
;         EBT[j0 * 40 + t] = (bf16_t)(gb & 0xFFFFu); EBT[(j0 + 1) * 40 + t] = (bf16_t)(gb >> 16); EBT[j0 * 40 + 16 + t] = (bf16_t)(gk & 0xFFFFu); EBT[(j0 + 1) * 40 + 16 + t] = (bf16_t)(gk >> 16);
;         UV[j0 * 40 + 16 + t] = (bf16_t)(gv & 0xFFFFu); UV[(j0 + 1) * 40 + 16 + t] = (bf16_t)(gv >> 16); UV[j0 * 40 + t] = 0; UV[(j0 + 1) * 40 + t] = 0;
;         if (tidv < 64) GT[tidv] = gg; };
.Lrw_w3_done:
	ds_write2st64_b32 v48, v71, v76 offset1:9
	ds_write2st64_b32 v48, v74, v75 offset0:18 offset1:27
	ds_write_b16 v47, v74 offset:9216
	ds_write_b16_d16_hi v47, v74 offset:9296
	ds_write_b16 v47, v75 offset:9248
	ds_write_b16_d16_hi v47, v75 offset:9328
	ds_write_b16 v47, v79 offset:14368
	ds_write_b16_d16_hi v47, v79 offset:14448
	ds_write_b16 v47, v5 offset:14336
	ds_write_b16 v47, v5 offset:14416
	s_and_saveexec_b64 s[78:79], s[2:3]
	v_lshl_add_u32 v47, v44, 2, s89
	ds_write_b32 v47, v27 offset:23296
	s_or_b64 exec, exec, s[78:79]
	s_cmp_gt_u32 s86, 29
	s_cbranch_scc0 .LBB0_932

; #define LAS __attribute__((address_space(3)))
; __device__ __forceinline__ f32x4 mfma16(bf16x8 a, bf16x8 b, f32x4 c) { return __builtin_amdgcn_mfma_f32_16x16x32_bf16(a, b, c, 0, 0, 0); }
; __device__ __forceinline__ void lds_barrier() { asm volatile("s_waitcnt lgkmcnt(0)" ::: "memory"); __builtin_amdgcn_s_barrier(); asm volatile("" ::: "memory"); }
; __device__ __forceinline__ void rwkv_chunk_item(const P& p, const Ctx& c, int seg, int w, bool save) {
;     ...
;         lds_barrier();
;         if (c.wv >= 4) {
;             Zt = mfma16(*(const LAS bf16x8*)(UV + (mtq * 16 + l15) * 40 + quad * 8), *(const LAS bf16x8*)(NT + l15 * 40 + quad * 8), Zt);
;             *(LAS f32x4*)(YB + l15 * 68 + mtq * 16 + quad * 4) = Zt;
;         } else eload(ch);
.LBB0_896:
	s_waitcnt lgkmcnt(0)
	s_barrier
	s_mov_b64 s[2:3], -1
	s_and_b64 vcc, exec, s[68:69]
	v_lshlrev_b32_e32 v52, 3, v83
	s_cbranch_vccz .LBB0_898
	s_mov_b64 s[2:3], 0
	v_lshlrev_b32_e32 v45, 3, v83
.LBB0_898:
	s_andn2_b64 vcc, exec, s[2:3]
	s_cbranch_vccnz .LBB0_900
	v_add3_u32 v44, s88, v87, v85
	ds_read_b128 v[44:47], v44 offset:14336
	ds_read_b128 v[48:51], v86 offset:20736
	s_waitcnt lgkmcnt(0)
	v_mfma_f32_16x16x32_bf16 v[22:25], v[44:47], v[48:51], v[22:25]
	v_mul_lo_u32 v44, v82, s38
	v_add3_u32 v44, s39, v44, v85
	v_mov_b32_e32 v45, v52
	s_nop 4
	ds_write_b128 v44, v[22:25] offset:60672
	v_mov_b32_e32 v44, v2
	v_mov_b64_e32 v[46:47], v[42:43]
	v_mov_b64_e32 v[48:49], v[40:41]
	v_mov_b64_e32 v[50:51], v[38:39]

; __device__ __forceinline__ void rwkv_chunk_item(const P& p, const Ctx& c, int seg, int w, bool save) {
;     ...
;     auto eload = [&](int ch) { const size_t rr = (size_t)b * SEGT + ch * 16 + et;
;         e_g = *(const u32x2*)(SG + rr * DMIX + ech); e_v = *(const u32x2*)(SV + rr * DMIX + ech); e_z = *(const u32x2*)(P2 + rr * P2W + 512 + ech); e_rkr = BRKR[(rr * 24 + hh) * 4 + 2]; };
;     ...
;     for (int ch = 0; ch < SEGT / 16; ++ch) {
;         const int pb = ch & 1;
;         int tidv = c.tid, l15 = l15c, quad = quadc; asm volatile("" : "+v"(tidv), "+v"(l15), "+v"(quad));
.LBB0_929:
	s_add_i32 s86, s86, 1
	s_add_u32 s76, s76, 16
	s_mov_b64 s[2:3], 0x14000
	s_addc_u32 s77, s77, 0
	v_lshl_add_u64 v[34:35], v[34:35], 0, s[2:3]
	s_mov_b64 s[2:3], 0xc000
	v_add_u32_e32 v4, 16, v4
	v_lshl_add_u64 v[32:33], v[32:33], 0, s[52:53]
	s_cmp_eq_u32 s86, 32
	v_lshl_add_u64 v[36:37], v[36:37], 0, s[2:3]
	s_and_b64 vcc, exec, s[68:69]
	s_cbranch_vccz .Lrw_bot_done
	s_cmp_gt_u32 s86, 30
	s_cbranch_scc1 .Lrw_bot_w0
	s_waitcnt vmcnt(5)
	s_branch .Lrw_bot_copy

; __device__ __forceinline__ void rwkv_chunk_item(const P& p, const Ctx& c, int seg, int w, bool save) {
;     ...
;     auto eload = [&](int ch) { const size_t rr = (size_t)b * SEGT + ch * 16 + et;
;         e_g = *(const u32x2*)(SG + rr * DMIX + ech); e_v = *(const u32x2*)(SV + rr * DMIX + ech); e_z = *(const u32x2*)(P2 + rr * P2W + 512 + ech); e_rkr = BRKR[(rr * 24 + hh) * 4 + 2]; };
.Lrw_bot_copy:
	v_mov_b64_e32 v[38:39], v[104:105]
	v_mov_b64_e32 v[40:41], v[106:107]
	v_mov_b64_e32 v[42:43], v[108:109]
	v_mov_b32_e32 v2, v110
	v_mov_b64_e32 v[50:51], v[104:105]
	v_mov_b64_e32 v[48:49], v[106:107]
	v_mov_b64_e32 v[46:47], v[108:109]
	v_mov_b32_e32 v44, v110
.Lrw_bot_done:
	s_cmp_eq_u32 s86, 32
	s_cbranch_scc1 .LBB0_935
	s_branch .LBB0_886
